# 4-phase K-loop without any s_setprio flips
# baseline (speedup 1.0000x reference)
.LBB0_919:
	s_add_i32 s42, s20, 2
	s_add_u32 s24, s18, 0x80
	s_addc_u32 s21, s19, 0
	s_add_i32 s43, 0, 0x10000
	v_add_u32_e32 v0, s43, v211
	s_waitcnt lgkmcnt(0)
	ds_read_b128 v[130:133], v0
	ds_read_b128 v[134:137], v0 offset:1024
	ds_read_b128 v[138:141], v0 offset:2048
	ds_read_b128 v[142:145], v0 offset:3072
	s_cmp_eq_u32 s66, s20
	s_cselect_b32 s20, s74, s24
	s_cselect_b32 s21, s75, s21
	s_cselect_b32 s25, s77, s39
	s_cselect_b32 s24, s76, s38
	s_add_i32 s44, 0, 0x14000
	v_add_u32_e32 v0, s44, v211
	v_lshl_add_u64 v[198:199], s[18:19], 0, v[184:185]
	s_add_i32 m0, s31, 0xc000
	ds_read_b128 v[232:235], v0
	ds_read_b128 v[236:239], v0 offset:1024
	ds_read_b128 v[240:243], v0 offset:2048
	ds_read_b128 v[244:247], v0 offset:3072
	global_load_lds_dwordx4 v[198:199], off
	v_lshl_add_u64 v[198:199], s[18:19], 0, v[182:183]
	s_add_i32 m0, s31, 0xe000
	s_nop 0
	global_load_lds_dwordx4 v[198:199], off
	ds_read_b128 v[146:149], v212
	ds_read_b128 v[150:153], v212 offset:1024
	ds_read_b128 v[154:157], v212 offset:2048
	ds_read_b128 v[158:161], v212 offset:3072
	ds_read_b128 v[186:189], v212 offset:4096
	ds_read_b128 v[190:193], v212 offset:5120
	s_waitcnt lgkmcnt(12)
	ds_read_b128 v[194:197], v212 offset:6144
	ds_read_b128 v[214:217], v212 offset:7168
	s_waitcnt vmcnt(8) lgkmcnt(0)
	s_barrier
	v_mfma_f32_16x16x32_bf16 v[126:129], v[130:133], v[146:149], v[126:129]
	v_mfma_f32_16x16x32_bf16 v[122:125], v[138:141], v[146:149], v[122:125]
	v_mfma_f32_16x16x32_bf16 v[110:113], v[130:133], v[154:157], v[110:113]
	v_mfma_f32_16x16x32_bf16 v[106:109], v[138:141], v[154:157], v[106:109]
	v_mfma_f32_16x16x32_bf16 v[94:97], v[130:133], v[186:189], v[94:97]
	v_mfma_f32_16x16x32_bf16 v[90:93], v[138:141], v[186:189], v[90:93]
	v_mfma_f32_16x16x32_bf16 v[78:81], v[130:133], v[194:197], v[78:81]
	v_mfma_f32_16x16x32_bf16 v[74:77], v[138:141], v[194:197], v[74:77]
	v_mfma_f32_16x16x32_bf16 v[126:129], v[134:137], v[150:153], v[126:129]
	v_mfma_f32_16x16x32_bf16 v[122:125], v[142:145], v[150:153], v[122:125]
	v_mfma_f32_16x16x32_bf16 v[110:113], v[134:137], v[158:161], v[110:113]
	v_mfma_f32_16x16x32_bf16 v[106:109], v[142:145], v[158:161], v[106:109]
	v_mfma_f32_16x16x32_bf16 v[94:97], v[134:137], v[190:193], v[94:97]
	v_mfma_f32_16x16x32_bf16 v[90:93], v[142:145], v[190:193], v[90:93]
	v_mfma_f32_16x16x32_bf16 v[78:81], v[134:137], v[214:217], v[78:81]
	v_mfma_f32_16x16x32_bf16 v[74:77], v[142:145], v[214:217], v[74:77]
	v_mfma_f32_16x16x32_bf16 v[118:121], v[232:235], v[146:149], v[118:121]
	v_mfma_f32_16x16x32_bf16 v[114:117], v[240:243], v[146:149], v[114:117]
	v_mfma_f32_16x16x32_bf16 v[102:105], v[232:235], v[154:157], v[102:105]
	v_mfma_f32_16x16x32_bf16 v[98:101], v[240:243], v[154:157], v[98:101]
	v_mfma_f32_16x16x32_bf16 v[86:89], v[232:235], v[186:189], v[86:89]
	v_mfma_f32_16x16x32_bf16 v[82:85], v[240:243], v[186:189], v[82:85]
	v_mfma_f32_16x16x32_bf16 v[70:73], v[232:235], v[194:197], v[70:73]
	v_mfma_f32_16x16x32_bf16 v[66:69], v[240:243], v[194:197], v[66:69]
	v_mfma_f32_16x16x32_bf16 v[118:121], v[236:239], v[150:153], v[118:121]
	v_mfma_f32_16x16x32_bf16 v[114:117], v[244:247], v[150:153], v[114:117]
	v_mfma_f32_16x16x32_bf16 v[102:105], v[236:239], v[158:161], v[102:105]
	v_mfma_f32_16x16x32_bf16 v[98:101], v[244:247], v[158:161], v[98:101]
	v_mfma_f32_16x16x32_bf16 v[86:89], v[236:239], v[190:193], v[86:89]
	v_mfma_f32_16x16x32_bf16 v[82:85], v[244:247], v[190:193], v[82:85]
	v_mfma_f32_16x16x32_bf16 v[70:73], v[236:239], v[214:217], v[70:73]
	v_mfma_f32_16x16x32_bf16 v[66:69], v[244:247], v[214:217], v[66:69]
	s_barrier
	ds_read_b128 v[146:149], v212 offset:16384
	ds_read_b128 v[150:153], v212 offset:17408
	ds_read_b128 v[154:157], v212 offset:18432
	ds_read_b128 v[158:161], v212 offset:19456
	ds_read_b128 v[186:189], v212 offset:20480
	ds_read_b128 v[190:193], v212 offset:21504
	ds_read_b128 v[194:197], v212 offset:22528
	ds_read_b128 v[214:217], v212 offset:23552
	s_add_i32 s43, s43, s30
	v_lshl_add_u64 v[198:199], s[24:25], 0, v[170:171]
	s_mov_b32 m0, s43
	v_lshl_add_u64 v[218:219], s[24:25], 0, v[174:175]
	global_load_lds_dwordx4 v[198:199], off
	s_add_i32 m0, s43, 0x2000
	s_nop 0
	global_load_lds_dwordx4 v[218:219], off
	s_mov_b32 m0, s31
	v_lshl_add_u64 v[248:249], s[20:21], 0, v[168:169]
	v_lshl_add_u64 v[250:251], s[20:21], 0, v[172:173]
	global_load_lds_dwordx4 v[248:249], off
	s_mov_b32 m0, s95
	s_nop 0
	global_load_lds_dwordx4 v[250:251], off
	s_add_u32 s24, s24, s60
	s_addc_u32 s25, s25, 0
	s_add_i32 s43, s44, s30
	v_lshl_add_u64 v[226:227], s[24:25], 0, v[170:171]
	s_mov_b32 m0, s43
	v_lshl_add_u64 v[228:229], s[24:25], 0, v[174:175]
	global_load_lds_dwordx4 v[226:227], off
	s_add_i32 m0, s43, 0x2000
	s_nop 0
	global_load_lds_dwordx4 v[228:229], off
	s_waitcnt vmcnt(8) lgkmcnt(0)
	s_barrier
	v_mfma_f32_16x16x32_bf16 v[62:65], v[130:133], v[146:149], v[62:65]
	v_mfma_f32_16x16x32_bf16 v[58:61], v[138:141], v[146:149], v[58:61]
	v_mfma_f32_16x16x32_bf16 v[46:49], v[130:133], v[154:157], v[46:49]
	v_mfma_f32_16x16x32_bf16 v[42:45], v[138:141], v[154:157], v[42:45]
	v_mfma_f32_16x16x32_bf16 v[30:33], v[130:133], v[186:189], v[30:33]
	v_mfma_f32_16x16x32_bf16 v[26:29], v[138:141], v[186:189], v[26:29]
	v_mfma_f32_16x16x32_bf16 v[14:17], v[130:133], v[194:197], v[14:17]
	v_mfma_f32_16x16x32_bf16 v[10:13], v[138:141], v[194:197], v[10:13]
	v_mfma_f32_16x16x32_bf16 v[62:65], v[134:137], v[150:153], v[62:65]
	v_mfma_f32_16x16x32_bf16 v[58:61], v[142:145], v[150:153], v[58:61]
	v_mfma_f32_16x16x32_bf16 v[46:49], v[134:137], v[158:161], v[46:49]
	v_mfma_f32_16x16x32_bf16 v[42:45], v[142:145], v[158:161], v[42:45]
	v_mfma_f32_16x16x32_bf16 v[30:33], v[134:137], v[190:193], v[30:33]
	v_mfma_f32_16x16x32_bf16 v[26:29], v[142:145], v[190:193], v[26:29]
	v_mfma_f32_16x16x32_bf16 v[14:17], v[134:137], v[214:217], v[14:17]
	v_mfma_f32_16x16x32_bf16 v[10:13], v[142:145], v[214:217], v[10:13]
	v_mfma_f32_16x16x32_bf16 v[54:57], v[232:235], v[146:149], v[54:57]
	v_mfma_f32_16x16x32_bf16 v[50:53], v[240:243], v[146:149], v[50:53]
	v_mfma_f32_16x16x32_bf16 v[38:41], v[232:235], v[154:157], v[38:41]
	v_mfma_f32_16x16x32_bf16 v[34:37], v[240:243], v[154:157], v[34:37]
	v_mfma_f32_16x16x32_bf16 v[22:25], v[232:235], v[186:189], v[22:25]
	v_mfma_f32_16x16x32_bf16 v[18:21], v[240:243], v[186:189], v[18:21]
	v_mfma_f32_16x16x32_bf16 v[6:9], v[232:235], v[194:197], v[6:9]
	v_mfma_f32_16x16x32_bf16 v[2:5], v[240:243], v[194:197], v[2:5]
	v_mfma_f32_16x16x32_bf16 v[54:57], v[236:239], v[150:153], v[54:57]
	v_mfma_f32_16x16x32_bf16 v[50:53], v[244:247], v[150:153], v[50:53]
	v_mfma_f32_16x16x32_bf16 v[38:41], v[236:239], v[158:161], v[38:41]
	v_mfma_f32_16x16x32_bf16 v[34:37], v[244:247], v[158:161], v[34:37]
	v_mfma_f32_16x16x32_bf16 v[22:25], v[236:239], v[190:193], v[22:25]
	v_mfma_f32_16x16x32_bf16 v[18:21], v[244:247], v[190:193], v[18:21]
	v_mfma_f32_16x16x32_bf16 v[6:9], v[236:239], v[214:217], v[6:9]
	v_mfma_f32_16x16x32_bf16 v[2:5], v[244:247], v[214:217], v[2:5]
	s_barrier
	s_add_u32 s20, s20, s60
	s_addc_u32 s21, s21, 0
	s_mov_b32 m0, s8
	v_lshl_add_u64 v[232:233], s[20:21], 0, v[168:169]
	s_add_i32 s24, 0, 0x18000
	v_add_u32_e32 v0, s24, v211
	global_load_lds_dwordx4 v[232:233], off
	v_lshl_add_u64 v[232:233], s[20:21], 0, v[172:173]
	s_mov_b32 m0, s9
	s_nop 0
	global_load_lds_dwordx4 v[232:233], off
	ds_read_b128 v[130:133], v0
	ds_read_b128 v[134:137], v0 offset:1024
	ds_read_b128 v[138:141], v0 offset:2048
	ds_read_b128 v[142:145], v0 offset:3072
	s_add_i32 s20, 0, 0x1c000
	s_add_i32 s21, s24, s30
	v_add_u32_e32 v0, s20, v211
	ds_read_b128 v[232:235], v0
	ds_read_b128 v[236:239], v0 offset:1024
	ds_read_b128 v[240:243], v0 offset:2048
	ds_read_b128 v[244:247], v0 offset:3072
	ds_read_b128 v[146:149], v212 offset:32768
	ds_read_b128 v[150:153], v212 offset:33792
	ds_read_b128 v[154:157], v212 offset:34816
	ds_read_b128 v[158:161], v212 offset:35840
	ds_read_b128 v[186:189], v212 offset:36864
	ds_read_b128 v[190:193], v212 offset:37888
	s_waitcnt lgkmcnt(12)
	ds_read_b128 v[194:197], v212 offset:38912
	ds_read_b128 v[214:217], v212 offset:39936
	s_waitcnt vmcnt(8) lgkmcnt(0)
	s_barrier
	v_mfma_f32_16x16x32_bf16 v[126:129], v[130:133], v[146:149], v[126:129]
	v_mfma_f32_16x16x32_bf16 v[122:125], v[138:141], v[146:149], v[122:125]
	v_mfma_f32_16x16x32_bf16 v[110:113], v[130:133], v[154:157], v[110:113]
	v_mfma_f32_16x16x32_bf16 v[106:109], v[138:141], v[154:157], v[106:109]
	v_mfma_f32_16x16x32_bf16 v[94:97], v[130:133], v[186:189], v[94:97]
	v_mfma_f32_16x16x32_bf16 v[90:93], v[138:141], v[186:189], v[90:93]
	v_mfma_f32_16x16x32_bf16 v[78:81], v[130:133], v[194:197], v[78:81]
	v_mfma_f32_16x16x32_bf16 v[74:77], v[138:141], v[194:197], v[74:77]
	v_mfma_f32_16x16x32_bf16 v[126:129], v[134:137], v[150:153], v[126:129]
	v_mfma_f32_16x16x32_bf16 v[122:125], v[142:145], v[150:153], v[122:125]
	v_mfma_f32_16x16x32_bf16 v[110:113], v[134:137], v[158:161], v[110:113]
	v_mfma_f32_16x16x32_bf16 v[106:109], v[142:145], v[158:161], v[106:109]
	v_mfma_f32_16x16x32_bf16 v[94:97], v[134:137], v[190:193], v[94:97]
	v_mfma_f32_16x16x32_bf16 v[90:93], v[142:145], v[190:193], v[90:93]
	v_mfma_f32_16x16x32_bf16 v[78:81], v[134:137], v[214:217], v[78:81]
	v_mfma_f32_16x16x32_bf16 v[74:77], v[142:145], v[214:217], v[74:77]
	v_mfma_f32_16x16x32_bf16 v[118:121], v[232:235], v[146:149], v[118:121]
	v_mfma_f32_16x16x32_bf16 v[114:117], v[240:243], v[146:149], v[114:117]
	v_mfma_f32_16x16x32_bf16 v[102:105], v[232:235], v[154:157], v[102:105]
	v_mfma_f32_16x16x32_bf16 v[98:101], v[240:243], v[154:157], v[98:101]
	v_mfma_f32_16x16x32_bf16 v[86:89], v[232:235], v[186:189], v[86:89]
	v_mfma_f32_16x16x32_bf16 v[82:85], v[240:243], v[186:189], v[82:85]
	v_mfma_f32_16x16x32_bf16 v[70:73], v[232:235], v[194:197], v[70:73]
	v_mfma_f32_16x16x32_bf16 v[66:69], v[240:243], v[194:197], v[66:69]
	v_mfma_f32_16x16x32_bf16 v[118:121], v[236:239], v[150:153], v[118:121]
	v_mfma_f32_16x16x32_bf16 v[114:117], v[244:247], v[150:153], v[114:117]
	v_mfma_f32_16x16x32_bf16 v[102:105], v[236:239], v[158:161], v[102:105]
	v_mfma_f32_16x16x32_bf16 v[98:101], v[244:247], v[158:161], v[98:101]
	v_mfma_f32_16x16x32_bf16 v[86:89], v[236:239], v[190:193], v[86:89]
	v_mfma_f32_16x16x32_bf16 v[82:85], v[244:247], v[190:193], v[82:85]
	v_mfma_f32_16x16x32_bf16 v[70:73], v[236:239], v[214:217], v[70:73]
	v_mfma_f32_16x16x32_bf16 v[66:69], v[244:247], v[214:217], v[66:69]
	s_barrier
	ds_read_b128 v[146:149], v212 offset:49152
	ds_read_b128 v[150:153], v212 offset:50176
	ds_read_b128 v[154:157], v212 offset:51200
	ds_read_b128 v[158:161], v212 offset:52224
	ds_read_b128 v[186:189], v212 offset:53248
	ds_read_b128 v[190:193], v212 offset:54272
	ds_read_b128 v[194:197], v212 offset:55296
	ds_read_b128 v[214:217], v212 offset:56320
	v_lshl_add_u64 v[198:199], v[198:199], 0, s[16:17]
	s_mov_b32 m0, s21
	v_lshl_add_u64 v[218:219], v[218:219], 0, s[16:17]
	global_load_lds_dwordx4 v[198:199], off
	s_add_i32 m0, s21, 0x2000
	s_nop 0
	global_load_lds_dwordx4 v[218:219], off
	s_mov_b32 m0, s97
	v_lshl_add_u64 v[248:249], v[248:249], 0, s[16:17]
	v_lshl_add_u64 v[250:251], v[250:251], 0, s[16:17]
	global_load_lds_dwordx4 v[248:249], off
	s_mov_b32 m0, s90
	s_nop 0
	global_load_lds_dwordx4 v[250:251], off
	s_add_i32 s20, s20, s30
	v_lshl_add_u64 v[226:227], v[226:227], 0, s[16:17]
	s_mov_b32 m0, s20
	v_lshl_add_u64 v[228:229], v[228:229], 0, s[16:17]
	global_load_lds_dwordx4 v[226:227], off
	s_add_i32 m0, s20, 0x2000
	s_nop 0
	global_load_lds_dwordx4 v[228:229], off
	s_waitcnt vmcnt(8) lgkmcnt(0)
	s_barrier
	v_mfma_f32_16x16x32_bf16 v[62:65], v[130:133], v[146:149], v[62:65]
	v_mfma_f32_16x16x32_bf16 v[58:61], v[138:141], v[146:149], v[58:61]
	v_mfma_f32_16x16x32_bf16 v[46:49], v[130:133], v[154:157], v[46:49]
	v_mfma_f32_16x16x32_bf16 v[42:45], v[138:141], v[154:157], v[42:45]
	v_mfma_f32_16x16x32_bf16 v[30:33], v[130:133], v[186:189], v[30:33]
	v_mfma_f32_16x16x32_bf16 v[26:29], v[138:141], v[186:189], v[26:29]
	v_mfma_f32_16x16x32_bf16 v[14:17], v[130:133], v[194:197], v[14:17]
	v_mfma_f32_16x16x32_bf16 v[10:13], v[138:141], v[194:197], v[10:13]
	v_mfma_f32_16x16x32_bf16 v[62:65], v[134:137], v[150:153], v[62:65]
	v_mfma_f32_16x16x32_bf16 v[58:61], v[142:145], v[150:153], v[58:61]
	v_mfma_f32_16x16x32_bf16 v[46:49], v[134:137], v[158:161], v[46:49]
	v_mfma_f32_16x16x32_bf16 v[42:45], v[142:145], v[158:161], v[42:45]
	v_mfma_f32_16x16x32_bf16 v[30:33], v[134:137], v[190:193], v[30:33]
	v_mfma_f32_16x16x32_bf16 v[26:29], v[142:145], v[190:193], v[26:29]
	v_mfma_f32_16x16x32_bf16 v[14:17], v[134:137], v[214:217], v[14:17]
	v_mfma_f32_16x16x32_bf16 v[10:13], v[142:145], v[214:217], v[10:13]
	v_mfma_f32_16x16x32_bf16 v[54:57], v[232:235], v[146:149], v[54:57]
	v_mfma_f32_16x16x32_bf16 v[50:53], v[240:243], v[146:149], v[50:53]
	v_mfma_f32_16x16x32_bf16 v[38:41], v[232:235], v[154:157], v[38:41]
	v_mfma_f32_16x16x32_bf16 v[34:37], v[240:243], v[154:157], v[34:37]
	v_mfma_f32_16x16x32_bf16 v[22:25], v[232:235], v[186:189], v[22:25]
	v_mfma_f32_16x16x32_bf16 v[18:21], v[240:243], v[186:189], v[18:21]
	v_mfma_f32_16x16x32_bf16 v[6:9], v[232:235], v[194:197], v[6:9]
	v_mfma_f32_16x16x32_bf16 v[2:5], v[240:243], v[194:197], v[2:5]
	v_mfma_f32_16x16x32_bf16 v[54:57], v[236:239], v[150:153], v[54:57]
	v_mfma_f32_16x16x32_bf16 v[50:53], v[244:247], v[150:153], v[50:53]
	v_mfma_f32_16x16x32_bf16 v[38:41], v[236:239], v[158:161], v[38:41]
	v_mfma_f32_16x16x32_bf16 v[34:37], v[244:247], v[158:161], v[34:37]
	v_mfma_f32_16x16x32_bf16 v[22:25], v[236:239], v[190:193], v[22:25]
	v_mfma_f32_16x16x32_bf16 v[18:21], v[244:247], v[190:193], v[18:21]
	v_mfma_f32_16x16x32_bf16 v[6:9], v[236:239], v[214:217], v[6:9]
	v_mfma_f32_16x16x32_bf16 v[2:5], v[244:247], v[214:217], v[2:5]
	s_add_u32 s38, s38, 0x100
	s_addc_u32 s39, s39, 0
	s_add_u32 s18, s18, 0x100
	s_addc_u32 s19, s19, 0
	s_cmp_ge_u32 s42, s91
	s_mov_b32 s20, s42
	s_barrier
	s_cbranch_scc0 .LBB0_919
	s_branch .Lkloop_done
.Lkloop_narrow:
	s_add_i32 s42, s20, 2
	s_add_u32 s24, s18, 0x80
	s_addc_u32 s21, s19, 0
	s_add_i32 s43, 0, 0x10000
	v_add_u32_e32 v0, s43, v211
	s_waitcnt lgkmcnt(0)
	ds_read_b128 v[130:133], v0
	ds_read_b128 v[134:137], v0 offset:1024
	ds_read_b128 v[138:141], v0 offset:2048
	ds_read_b128 v[142:145], v0 offset:3072
	s_cmp_eq_u32 s66, s20
	s_cselect_b32 s20, s74, s24
	s_cselect_b32 s21, s75, s21
	s_cselect_b32 s25, s77, s39
	s_cselect_b32 s24, s76, s38
	s_add_i32 s44, 0, 0x14000
	v_add_u32_e32 v0, s44, v211
	v_lshl_add_u64 v[198:199], s[18:19], 0, v[184:185]
	s_add_i32 m0, s31, 0xc000
	global_load_lds_dwordx4 v[198:199], off
	v_lshl_add_u64 v[198:199], s[18:19], 0, v[182:183]
	s_add_i32 m0, s31, 0xe000
	s_nop 0
	global_load_lds_dwordx4 v[198:199], off
	ds_read_b128 v[146:149], v212
	ds_read_b128 v[150:153], v212 offset:1024
	ds_read_b128 v[154:157], v212 offset:2048
	ds_read_b128 v[158:161], v212 offset:3072
	ds_read_b128 v[186:189], v212 offset:4096
	ds_read_b128 v[190:193], v212 offset:5120
	s_waitcnt lgkmcnt(12)
	ds_read_b128 v[194:197], v212 offset:6144
	ds_read_b128 v[214:217], v212 offset:7168
	s_waitcnt vmcnt(8) lgkmcnt(0)
	s_barrier
	v_mfma_f32_16x16x32_bf16 v[126:129], v[130:133], v[146:149], v[126:129]
	v_mfma_f32_16x16x32_bf16 v[122:125], v[138:141], v[146:149], v[122:125]
	v_mfma_f32_16x16x32_bf16 v[110:113], v[130:133], v[154:157], v[110:113]
	v_mfma_f32_16x16x32_bf16 v[106:109], v[138:141], v[154:157], v[106:109]
	v_mfma_f32_16x16x32_bf16 v[94:97], v[130:133], v[186:189], v[94:97]
	v_mfma_f32_16x16x32_bf16 v[90:93], v[138:141], v[186:189], v[90:93]
	v_mfma_f32_16x16x32_bf16 v[78:81], v[130:133], v[194:197], v[78:81]
	v_mfma_f32_16x16x32_bf16 v[74:77], v[138:141], v[194:197], v[74:77]
	v_mfma_f32_16x16x32_bf16 v[126:129], v[134:137], v[150:153], v[126:129]
	v_mfma_f32_16x16x32_bf16 v[122:125], v[142:145], v[150:153], v[122:125]
	v_mfma_f32_16x16x32_bf16 v[110:113], v[134:137], v[158:161], v[110:113]
	v_mfma_f32_16x16x32_bf16 v[106:109], v[142:145], v[158:161], v[106:109]
	v_mfma_f32_16x16x32_bf16 v[94:97], v[134:137], v[190:193], v[94:97]
	v_mfma_f32_16x16x32_bf16 v[90:93], v[142:145], v[190:193], v[90:93]
	v_mfma_f32_16x16x32_bf16 v[78:81], v[134:137], v[214:217], v[78:81]
	v_mfma_f32_16x16x32_bf16 v[74:77], v[142:145], v[214:217], v[74:77]
	s_barrier
	ds_read_b128 v[146:149], v212 offset:16384
	ds_read_b128 v[150:153], v212 offset:17408
	ds_read_b128 v[154:157], v212 offset:18432
	ds_read_b128 v[158:161], v212 offset:19456
	ds_read_b128 v[186:189], v212 offset:20480
	ds_read_b128 v[190:193], v212 offset:21504
	ds_read_b128 v[194:197], v212 offset:22528
	ds_read_b128 v[214:217], v212 offset:23552
	s_add_i32 s43, s43, s30
	v_lshl_add_u64 v[198:199], s[24:25], 0, v[170:171]
	s_mov_b32 m0, s43
	v_lshl_add_u64 v[218:219], s[24:25], 0, v[174:175]
	global_load_lds_dwordx4 v[198:199], off
	s_add_i32 m0, s43, 0x2000
	s_nop 0
	global_load_lds_dwordx4 v[218:219], off
	s_mov_b32 m0, s31
	v_lshl_add_u64 v[248:249], s[20:21], 0, v[168:169]
	v_lshl_add_u64 v[250:251], s[20:21], 0, v[172:173]
	global_load_lds_dwordx4 v[248:249], off
	s_mov_b32 m0, s95
	s_nop 0
	global_load_lds_dwordx4 v[250:251], off
	s_add_u32 s24, s24, s60
	s_addc_u32 s25, s25, 0
	s_add_i32 s43, s44, s30
	v_lshl_add_u64 v[226:227], s[24:25], 0, v[170:171]
	s_mov_b32 m0, s43
	v_lshl_add_u64 v[228:229], s[24:25], 0, v[174:175]
	global_load_lds_dwordx4 v[226:227], off
	s_add_i32 m0, s43, 0x2000
	s_nop 0
	global_load_lds_dwordx4 v[228:229], off
	s_waitcnt vmcnt(8) lgkmcnt(0)
	s_barrier
	v_mfma_f32_16x16x32_bf16 v[62:65], v[130:133], v[146:149], v[62:65]
	v_mfma_f32_16x16x32_bf16 v[58:61], v[138:141], v[146:149], v[58:61]
	v_mfma_f32_16x16x32_bf16 v[46:49], v[130:133], v[154:157], v[46:49]
	v_mfma_f32_16x16x32_bf16 v[42:45], v[138:141], v[154:157], v[42:45]
	v_mfma_f32_16x16x32_bf16 v[30:33], v[130:133], v[186:189], v[30:33]
	v_mfma_f32_16x16x32_bf16 v[26:29], v[138:141], v[186:189], v[26:29]
	v_mfma_f32_16x16x32_bf16 v[14:17], v[130:133], v[194:197], v[14:17]
	v_mfma_f32_16x16x32_bf16 v[10:13], v[138:141], v[194:197], v[10:13]
	v_mfma_f32_16x16x32_bf16 v[62:65], v[134:137], v[150:153], v[62:65]
	v_mfma_f32_16x16x32_bf16 v[58:61], v[142:145], v[150:153], v[58:61]
	v_mfma_f32_16x16x32_bf16 v[46:49], v[134:137], v[158:161], v[46:49]
	v_mfma_f32_16x16x32_bf16 v[42:45], v[142:145], v[158:161], v[42:45]
	v_mfma_f32_16x16x32_bf16 v[30:33], v[134:137], v[190:193], v[30:33]
	v_mfma_f32_16x16x32_bf16 v[26:29], v[142:145], v[190:193], v[26:29]
	v_mfma_f32_16x16x32_bf16 v[14:17], v[134:137], v[214:217], v[14:17]
	v_mfma_f32_16x16x32_bf16 v[10:13], v[142:145], v[214:217], v[10:13]
	s_barrier
	s_add_u32 s20, s20, s60
	s_addc_u32 s21, s21, 0
	s_mov_b32 m0, s8
	v_lshl_add_u64 v[232:233], s[20:21], 0, v[168:169]
	s_add_i32 s24, 0, 0x18000
	v_add_u32_e32 v0, s24, v211
	global_load_lds_dwordx4 v[232:233], off
	v_lshl_add_u64 v[232:233], s[20:21], 0, v[172:173]
	s_mov_b32 m0, s9
	s_nop 0
	global_load_lds_dwordx4 v[232:233], off
	ds_read_b128 v[130:133], v0
	ds_read_b128 v[134:137], v0 offset:1024
	ds_read_b128 v[138:141], v0 offset:2048
	ds_read_b128 v[142:145], v0 offset:3072
	s_add_i32 s20, 0, 0x1c000
	s_add_i32 s21, s24, s30
	v_add_u32_e32 v0, s20, v211
	ds_read_b128 v[146:149], v212 offset:32768
	ds_read_b128 v[150:153], v212 offset:33792
	ds_read_b128 v[154:157], v212 offset:34816
	ds_read_b128 v[158:161], v212 offset:35840
	ds_read_b128 v[186:189], v212 offset:36864
	ds_read_b128 v[190:193], v212 offset:37888
	s_waitcnt lgkmcnt(12)
	ds_read_b128 v[194:197], v212 offset:38912
	ds_read_b128 v[214:217], v212 offset:39936
	s_waitcnt vmcnt(8) lgkmcnt(0)
	s_barrier
	v_mfma_f32_16x16x32_bf16 v[126:129], v[130:133], v[146:149], v[126:129]
	v_mfma_f32_16x16x32_bf16 v[122:125], v[138:141], v[146:149], v[122:125]
	v_mfma_f32_16x16x32_bf16 v[110:113], v[130:133], v[154:157], v[110:113]
	v_mfma_f32_16x16x32_bf16 v[106:109], v[138:141], v[154:157], v[106:109]
	v_mfma_f32_16x16x32_bf16 v[94:97], v[130:133], v[186:189], v[94:97]
	v_mfma_f32_16x16x32_bf16 v[90:93], v[138:141], v[186:189], v[90:93]
	v_mfma_f32_16x16x32_bf16 v[78:81], v[130:133], v[194:197], v[78:81]
	v_mfma_f32_16x16x32_bf16 v[74:77], v[138:141], v[194:197], v[74:77]
	v_mfma_f32_16x16x32_bf16 v[126:129], v[134:137], v[150:153], v[126:129]
	v_mfma_f32_16x16x32_bf16 v[122:125], v[142:145], v[150:153], v[122:125]
	v_mfma_f32_16x16x32_bf16 v[110:113], v[134:137], v[158:161], v[110:113]
	v_mfma_f32_16x16x32_bf16 v[106:109], v[142:145], v[158:161], v[106:109]
	v_mfma_f32_16x16x32_bf16 v[94:97], v[134:137], v[190:193], v[94:97]
	v_mfma_f32_16x16x32_bf16 v[90:93], v[142:145], v[190:193], v[90:93]
	v_mfma_f32_16x16x32_bf16 v[78:81], v[134:137], v[214:217], v[78:81]
	v_mfma_f32_16x16x32_bf16 v[74:77], v[142:145], v[214:217], v[74:77]
	s_barrier
	ds_read_b128 v[146:149], v212 offset:49152
	ds_read_b128 v[150:153], v212 offset:50176
	ds_read_b128 v[154:157], v212 offset:51200
	ds_read_b128 v[158:161], v212 offset:52224
	ds_read_b128 v[186:189], v212 offset:53248
	ds_read_b128 v[190:193], v212 offset:54272
	ds_read_b128 v[194:197], v212 offset:55296
	ds_read_b128 v[214:217], v212 offset:56320
	v_lshl_add_u64 v[198:199], v[198:199], 0, s[16:17]
	s_mov_b32 m0, s21
	v_lshl_add_u64 v[218:219], v[218:219], 0, s[16:17]
	global_load_lds_dwordx4 v[198:199], off
	s_add_i32 m0, s21, 0x2000
	s_nop 0
	global_load_lds_dwordx4 v[218:219], off
	s_mov_b32 m0, s97
	v_lshl_add_u64 v[248:249], v[248:249], 0, s[16:17]
	v_lshl_add_u64 v[250:251], v[250:251], 0, s[16:17]
	global_load_lds_dwordx4 v[248:249], off
	s_mov_b32 m0, s90
	s_nop 0
	global_load_lds_dwordx4 v[250:251], off
	s_add_i32 s20, s20, s30
	v_lshl_add_u64 v[226:227], v[226:227], 0, s[16:17]
	s_mov_b32 m0, s20
	v_lshl_add_u64 v[228:229], v[228:229], 0, s[16:17]
	global_load_lds_dwordx4 v[226:227], off
	s_add_i32 m0, s20, 0x2000
	s_nop 0
	global_load_lds_dwordx4 v[228:229], off
	s_waitcnt vmcnt(8) lgkmcnt(0)
	s_barrier
	v_mfma_f32_16x16x32_bf16 v[62:65], v[130:133], v[146:149], v[62:65]
	v_mfma_f32_16x16x32_bf16 v[58:61], v[138:141], v[146:149], v[58:61]
	v_mfma_f32_16x16x32_bf16 v[46:49], v[130:133], v[154:157], v[46:49]
	v_mfma_f32_16x16x32_bf16 v[42:45], v[138:141], v[154:157], v[42:45]
	v_mfma_f32_16x16x32_bf16 v[30:33], v[130:133], v[186:189], v[30:33]
	v_mfma_f32_16x16x32_bf16 v[26:29], v[138:141], v[186:189], v[26:29]
	v_mfma_f32_16x16x32_bf16 v[14:17], v[130:133], v[194:197], v[14:17]
	v_mfma_f32_16x16x32_bf16 v[10:13], v[138:141], v[194:197], v[10:13]
	v_mfma_f32_16x16x32_bf16 v[62:65], v[134:137], v[150:153], v[62:65]
	v_mfma_f32_16x16x32_bf16 v[58:61], v[142:145], v[150:153], v[58:61]
	v_mfma_f32_16x16x32_bf16 v[46:49], v[134:137], v[158:161], v[46:49]
	v_mfma_f32_16x16x32_bf16 v[42:45], v[142:145], v[158:161], v[42:45]
	v_mfma_f32_16x16x32_bf16 v[30:33], v[134:137], v[190:193], v[30:33]
	v_mfma_f32_16x16x32_bf16 v[26:29], v[142:145], v[190:193], v[26:29]
	v_mfma_f32_16x16x32_bf16 v[14:17], v[134:137], v[214:217], v[14:17]
	v_mfma_f32_16x16x32_bf16 v[10:13], v[142:145], v[214:217], v[10:13]
	s_add_u32 s38, s38, 0x100
	s_addc_u32 s39, s39, 0
	s_add_u32 s18, s18, 0x100
	s_addc_u32 s19, s19, 0
	s_cmp_ge_u32 s42, s91
	s_mov_b32 s20, s42
	s_barrier
	s_cbranch_scc0 .Lkloop_narrow
